# P1 start: the four loads of the weight-table staging loop issued before the first wait
# baseline (speedup 1.0000x reference)
; #define LAS __attribute__((address_space(3)))
; template <int LO, int HI> __global__ void __launch_bounds__(NWAVES * 64, 2) fox_fwd(Args args) {
;     ...
;         LAS float* wf = (LAS float*)L;
;         for (int i = tid; i < 2048; i += NWAVES * 64) ((LAS f32x4*)wf)[i] = ((const f32x4*)WF)[i];
;         __syncthreads();
.LBB0_129:
	global_load_dwordx4 v[6:9], v[2:3], off
	v_lshl_add_u64 v[2:3], v[2:3], 0, s[12:13]
	global_load_dwordx4 v[10:13], v[2:3], off
	v_lshl_add_u64 v[2:3], v[2:3], 0, s[12:13]
	global_load_dwordx4 v[14:17], v[2:3], off
	v_lshl_add_u64 v[2:3], v[2:3], 0, s[12:13]
	global_load_dwordx4 v[18:21], v[2:3], off
	s_waitcnt vmcnt(3)
	ds_write_b128 v4, v[6:9]
	s_waitcnt vmcnt(2)
	ds_write_b128 v4, v[10:13] offset:8192
	s_waitcnt vmcnt(1)
	ds_write_b128 v4, v[14:17] offset:16384
	s_waitcnt vmcnt(0)
	ds_write_b128 v4, v[18:21] offset:24576
